# grid barrier wait: two poll loads kept in flight about half a round trip apart (was one load per round trip); release seen sooner
# baseline (speedup 1.0000x reference)
; DI unsigned xb_ld(unsigned* p) { return __hip_atomic_load(p, __ATOMIC_RELAXED, __HIP_MEMORY_SCOPE_AGENT); }
; DI unsigned xb_add(unsigned* p, unsigned v) { return __hip_atomic_fetch_add(p, v, __ATOMIC_RELAXED, __HIP_MEMORY_SCOPE_AGENT); }
; #define XB_SPIN(cond, bar) do { unsigned _sp = 0; while (cond) { __builtin_amdgcn_s_sleep(1); \
;     if ((++_sp & 255u) == 0u) { if (xb_ld(&(bar)[XB_TMO])) break; if (_sp > XB_SPIN_CAP) { atomicAdd(&(bar)[XB_TMO], 1u); break; } } } } while (0)
; template <bool FIRST>
; DI void xcd_barrier(XcdBarrier& b) {
;     ...
;     const unsigned bx = b.st[2];
;     if (FIRST) { unsigned n0, n1; xcd_barrier_complete(bar, bx, n0, n1); b.st[0] = n0; b.st[1] = n1; }
;     const unsigned nloc = b.st[0], nx = b.st[1];
;     const unsigned old = xb_add(&bar[XB_XSUB(bx)], 1u);
;     const unsigned gen = old / nloc;
;     if (old + 1u == (gen + 1u) * nloc) {
;       __builtin_amdgcn_fence(__ATOMIC_RELEASE, "agent");
;       asm volatile("s_waitcnt vmcnt(0)" ::: "memory");
;       const unsigned og = xb_add(&bar[XB_TOP], 1u);
;       const unsigned tg = og / nx;
;       if (og + 1u == (tg + 1u) * nx) xb_add(&bar[XB_TOPGEN], 1u);
;       else XB_SPIN(xb_ld(&bar[XB_TOPGEN]) == tg, bar);
;       __builtin_amdgcn_fence(__ATOMIC_ACQUIRE, "agent");
;       xb_add(&bar[XB_XGEN(bx)], 1u);
;       asm volatile("s_waitcnt vmcnt(0)" ::: "memory");
;     } else {
;       XB_SPIN(xb_ld(&bar[XB_XGEN(bx)]) == gen, bar);
;       __builtin_amdgcn_fence(__ATOMIC_ACQUIRE, "agent");
;       asm volatile("s_waitcnt vmcnt(0)" ::: "memory");
;     }
.LBB0_76:
	s_or_b64 exec, exec, s[0:1]
	s_cmp_eq_u32 s33, 15
	s_cselect_b64 vcc, -1, 0
	s_cmp_eq_u32 s33, 14
	s_cselect_b64 s[0:1], -1, 0
	s_cmp_eq_u32 s33, 13
	s_cselect_b64 s[4:5], -1, 0
	s_cmp_eq_u32 s33, 12
	s_cselect_b64 s[6:7], -1, 0
	s_cmp_eq_u32 s33, 11
	s_cselect_b64 s[8:9], -1, 0
	s_cmp_eq_u32 s33, 10
	s_cselect_b64 s[10:11], -1, 0
	s_cmp_eq_u32 s33, 9
	s_cselect_b64 s[12:13], -1, 0
	s_cmp_eq_u32 s33, 8
	s_cselect_b64 s[14:15], -1, 0
	s_cmp_eq_u32 s33, 7
	s_cselect_b64 s[16:17], -1, 0
	s_cmp_eq_u32 s33, 6
	s_cselect_b64 s[18:19], -1, 0
	s_cmp_eq_u32 s33, 5
	s_cselect_b64 s[20:21], -1, 0
	s_cmp_eq_u32 s33, 4
	s_cselect_b64 s[22:23], -1, 0
	s_cmp_eq_u32 s33, 3
	s_cselect_b64 s[24:25], -1, 0
	s_cmp_eq_u32 s33, 2
	s_cselect_b64 s[26:27], -1, 0
	s_cmp_eq_u32 s33, 1
	s_cselect_b64 s[28:29], -1, 0
	s_cmp_eq_u32 s33, 0
	s_cselect_b64 s[30:31], -1, 0
	v_cndmask_b32_e64 v0, 0, v25, s[30:31]
	v_cndmask_b32_e64 v0, v0, v10, s[28:29]
	v_cndmask_b32_e64 v0, v0, v11, s[26:27]
	v_cndmask_b32_e64 v0, v0, v12, s[24:25]
	v_cndmask_b32_e64 v0, v0, v13, s[22:23]
	v_cndmask_b32_e64 v0, v0, v14, s[20:21]
	v_cndmask_b32_e64 v0, v0, v15, s[18:19]
	v_cndmask_b32_e64 v0, v0, v16, s[16:17]
	v_cndmask_b32_e64 v0, v0, v17, s[14:15]
	v_cndmask_b32_e64 v0, v0, v18, s[12:13]
	v_cndmask_b32_e64 v0, v0, v19, s[10:11]
	v_cndmask_b32_e64 v0, v0, v20, s[8:9]
	v_cndmask_b32_e64 v0, v0, v21, s[6:7]
	v_cndmask_b32_e64 v0, v0, v22, s[4:5]
	v_cndmask_b32_e64 v0, v0, v23, s[0:1]
	v_cndmask_b32_e32 v0, v0, v24, vcc
	v_cmp_ne_u32_e32 vcc, 0, v25
	s_lshl_b32 s22, s33, 6
	s_mov_b32 s39, 0
	v_cndmask_b32_e64 v1, 0, 1, vcc
	v_cmp_ne_u32_e32 vcc, 0, v10
	s_add_i32 s38, s22, 0x500
	v_max_u32_e32 v0, 1, v0
	v_addc_co_u32_e32 v1, vcc, 0, v1, vcc
	v_cmp_ne_u32_e32 vcc, 0, v11
	s_lshl_b64 s[0:1], s[38:39], 2
	s_add_u32 s0, s34, s0
	v_cndmask_b32_e64 v2, 0, 1, vcc
	v_cmp_ne_u32_e32 vcc, 0, v12
	s_addc_u32 s1, s35, s1
	s_nop 0
	v_addc_co_u32_e32 v1, vcc, v1, v2, vcc
	v_cmp_ne_u32_e32 vcc, 0, v13
	s_nop 1
	v_cndmask_b32_e64 v2, 0, 1, vcc
	v_cmp_ne_u32_e32 vcc, 0, v14
	s_nop 1
	v_addc_co_u32_e32 v1, vcc, v1, v2, vcc
	v_cmp_ne_u32_e32 vcc, 0, v15
	s_nop 1
	v_cndmask_b32_e64 v2, 0, 1, vcc
	v_cmp_ne_u32_e32 vcc, 0, v16
	s_nop 1
	v_addc_co_u32_e32 v1, vcc, v1, v2, vcc
	v_cmp_ne_u32_e32 vcc, 0, v17
	s_nop 1
	v_cndmask_b32_e64 v2, 0, 1, vcc
	v_cmp_ne_u32_e32 vcc, 0, v18
	s_nop 1
	v_addc_co_u32_e32 v1, vcc, v1, v2, vcc
	v_cmp_ne_u32_e32 vcc, 0, v19
	s_nop 1
	v_cndmask_b32_e64 v2, 0, 1, vcc
	v_cmp_ne_u32_e32 vcc, 0, v20
	s_nop 1
	v_addc_co_u32_e32 v1, vcc, v1, v2, vcc
	v_cmp_ne_u32_e32 vcc, 0, v21
	s_nop 1
	v_cndmask_b32_e64 v2, 0, 1, vcc
	v_cmp_ne_u32_e32 vcc, 0, v22
	s_nop 1
	v_addc_co_u32_e32 v1, vcc, v1, v2, vcc
	v_cmp_ne_u32_e32 vcc, 0, v23
	s_nop 1
	v_cndmask_b32_e64 v2, 0, 1, vcc
	v_cmp_ne_u32_e32 vcc, 0, v24
	s_nop 1
	v_addc_co_u32_e32 v1, vcc, v1, v2, vcc
	v_mov_b32_e32 v2, 0x12000
	v_max_u32_e32 v1, 1, v1
	ds_write_b32 v2, v0
	v_mov_b32_e32 v0, 0x12004
	ds_write_b32 v0, v1
	ds_read_b32 v4, v2
	ds_read_b32 v1, v0
	v_mov_b64_e32 v[2:3], s[0:1]
	v_mov_b32_e32 v0, 1
	flat_atomic_add v2, v[2:3], v0 sc0
	s_waitcnt lgkmcnt(0)
	v_cvt_f32_u32_e32 v0, v4
	v_sub_u32_e32 v3, 0, v4
	v_rcp_iflag_f32_e32 v0, v0
	s_nop 0
	v_mul_f32_e32 v0, 0x4f7ffffe, v0
	v_cvt_u32_f32_e32 v0, v0
	v_mul_lo_u32 v3, v3, v0
	v_mul_hi_u32 v3, v0, v3
	v_add_u32_e32 v0, v0, v3
	s_waitcnt vmcnt(0)
	v_mul_hi_u32 v0, v2, v0
	v_mul_lo_u32 v3, v0, v4
	v_sub_u32_e32 v3, v2, v3
	v_add_u32_e32 v5, 1, v0
	v_cmp_ge_u32_e32 vcc, v3, v4
	v_add_u32_e32 v2, 1, v2
	s_nop 0
	v_cndmask_b32_e32 v0, v0, v5, vcc
	v_sub_u32_e32 v5, v3, v4
	v_cndmask_b32_e32 v3, v3, v5, vcc
	v_add_u32_e32 v5, 1, v0
	v_cmp_ge_u32_e32 vcc, v3, v4
	s_nop 1
	v_cndmask_b32_e32 v0, v0, v5, vcc
	v_mul_lo_u32 v3, v4, v0
	v_add_u32_e32 v3, v3, v4
	v_cmp_ne_u32_e32 vcc, v2, v3
	s_and_saveexec_b64 s[0:1], vcc
	s_xor_b64 s[0:1], exec, s[0:1]
	s_cbranch_execz .LBB0_89
	s_add_i32 s38, s22, 0x900
	s_add_u32 s6, s34, 0x3500
	s_addc_u32 s7, s35, 0
	v_mov_b64_e32 v[2:3], s[6:7]
	global_load_dword v1, v[2:3], off sc1
	s_waitcnt vmcnt(0) lgkmcnt(0)
	v_cmp_eq_u32_e32 vcc, v1, v0
	s_and_saveexec_b64 s[4:5], vcc
	s_cbranch_execz .LBB0_88
	global_load_dword v1, v[2:3], off sc1
	s_sleep 20
.Lsp_0:
	global_load_dword v4, v[2:3], off sc1
	s_waitcnt vmcnt(1)
	v_cmp_ne_u32_e32 vcc, v1, v0
	s_cbranch_vccnz .Lsp_d_0
	s_sleep 1
	global_load_dword v1, v[2:3], off sc1
	s_waitcnt vmcnt(1)
	v_cmp_ne_u32_e32 vcc, v4, v0
	s_cbranch_vccz .Lsp_0
.Lsp_d_0:
.LBB0_88:
	s_or_b64 exec, exec, s[4:5]
	s_waitcnt vmcnt(0) lgkmcnt(0)
	buffer_inv sc1
	s_waitcnt vmcnt(0)

; DI unsigned xb_ld(unsigned* p) { return __hip_atomic_load(p, __ATOMIC_RELAXED, __HIP_MEMORY_SCOPE_AGENT); }
; DI unsigned xb_add(unsigned* p, unsigned v) { return __hip_atomic_fetch_add(p, v, __ATOMIC_RELAXED, __HIP_MEMORY_SCOPE_AGENT); }
; #define XB_SPIN(cond, bar) do { unsigned _sp = 0; while (cond) { __builtin_amdgcn_s_sleep(1); \
;     if ((++_sp & 255u) == 0u) { if (xb_ld(&(bar)[XB_TMO])) break; if (_sp > XB_SPIN_CAP) { atomicAdd(&(bar)[XB_TMO], 1u); break; } } } } while (0)
; template <bool FIRST>
; DI void xcd_barrier(XcdBarrier& b) {
;     ...
;   if (threadIdx.x == 0) {
;     unsigned* bar = b.bar;
;     asm volatile("" : "+s"(bar));
;     __builtin_amdgcn_s_waitcnt(0);
;     const unsigned bx = b.st[2];
;     if (FIRST) { unsigned n0, n1; xcd_barrier_complete(bar, bx, n0, n1); b.st[0] = n0; b.st[1] = n1; }
;     const unsigned nloc = b.st[0], nx = b.st[1];
;     const unsigned old = xb_add(&bar[XB_XSUB(bx)], 1u);
;     const unsigned gen = old / nloc;
;     if (old + 1u == (gen + 1u) * nloc) {
;       __builtin_amdgcn_fence(__ATOMIC_RELEASE, "agent");
;       asm volatile("s_waitcnt vmcnt(0)" ::: "memory");
;       const unsigned og = xb_add(&bar[XB_TOP], 1u);
;       const unsigned tg = og / nx;
;       if (og + 1u == (tg + 1u) * nx) xb_add(&bar[XB_TOPGEN], 1u);
;       else XB_SPIN(xb_ld(&bar[XB_TOPGEN]) == tg, bar);
;       __builtin_amdgcn_fence(__ATOMIC_ACQUIRE, "agent");
;       xb_add(&bar[XB_XGEN(bx)], 1u);
;       asm volatile("s_waitcnt vmcnt(0)" ::: "memory");
;     } else {
;       XB_SPIN(xb_ld(&bar[XB_XGEN(bx)]) == gen, bar);
.LBB0_124:
	s_mul_i32 s0, s48, 6
	s_add_i32 s28, s0, 2
	s_cmp_ge_i32 s28, s59
	s_cbranch_scc1 .LBB0_156
	s_waitcnt vmcnt(0)
	s_waitcnt lgkmcnt(0)
	s_barrier
	s_and_saveexec_b64 s[0:1], s[60:61]
	s_cbranch_execz .LBB0_155
	v_readlane_b32 s4, v253, 1
	v_readlane_b32 s5, v253, 2
	s_waitcnt vmcnt(0) expcnt(0) lgkmcnt(0)
	ds_read_b32 v0, v163
	ds_read_b32 v4, v172
	ds_read_b32 v1, v173
	s_waitcnt lgkmcnt(2)
	v_readfirstlane_b32 s2, v0
	s_lshl_b32 s29, s2, 6
	s_add_i32 s2, s29, 0x500
	s_lshl_b64 s[6:7], s[2:3], 2
	s_add_u32 s6, s4, s6
	s_addc_u32 s7, s5, s7
	v_mov_b64_e32 v[2:3], s[6:7]
	flat_atomic_add v2, v[2:3], v174 sc0
	s_waitcnt lgkmcnt(0)
	v_cvt_f32_u32_e32 v0, v4
	v_sub_u32_e32 v3, 0, v4
	v_rcp_iflag_f32_e32 v0, v0
	s_nop 0
	v_mul_f32_e32 v0, 0x4f7ffffe, v0
	v_cvt_u32_f32_e32 v0, v0
	v_mul_lo_u32 v3, v3, v0
	v_mul_hi_u32 v3, v0, v3
	v_add_u32_e32 v0, v0, v3
	s_waitcnt vmcnt(0)
	v_mul_hi_u32 v0, v2, v0
	v_mul_lo_u32 v3, v0, v4
	v_sub_u32_e32 v3, v2, v3
	v_add_u32_e32 v5, 1, v0
	v_cmp_ge_u32_e32 vcc, v3, v4
	v_add_u32_e32 v2, 1, v2
	s_nop 0
	v_cndmask_b32_e32 v0, v0, v5, vcc
	v_sub_u32_e32 v5, v3, v4
	v_cndmask_b32_e32 v3, v3, v5, vcc
	v_add_u32_e32 v5, 1, v0
	v_cmp_ge_u32_e32 vcc, v3, v4
	s_nop 1
	v_cndmask_b32_e32 v0, v0, v5, vcc
	v_mul_lo_u32 v3, v4, v0
	v_add_u32_e32 v3, v3, v4
	v_cmp_ne_u32_e32 vcc, v2, v3
	s_and_saveexec_b64 s[6:7], vcc
	s_xor_b64 s[6:7], exec, s[6:7]
	s_cbranch_execz .LBB0_139
	s_add_i32 s2, s29, 0x900
	s_add_u32 s10, s4, 0x3500
	s_addc_u32 s11, s5, 0
	v_mov_b64_e32 v[2:3], s[10:11]
	global_load_dword v1, v[2:3], off sc1
	s_waitcnt vmcnt(0) lgkmcnt(0)
	v_cmp_eq_u32_e32 vcc, v1, v0
	s_and_saveexec_b64 s[8:9], vcc
	s_cbranch_execz .LBB0_138
	global_load_dword v1, v[2:3], off sc1
	s_sleep 20

; DI unsigned xb_ld(unsigned* p) { return __hip_atomic_load(p, __ATOMIC_RELAXED, __HIP_MEMORY_SCOPE_AGENT); }
; #define XB_SPIN(cond, bar) do { unsigned _sp = 0; while (cond) { __builtin_amdgcn_s_sleep(1); \
;     if ((++_sp & 255u) == 0u) { if (xb_ld(&(bar)[XB_TMO])) break; if (_sp > XB_SPIN_CAP) { atomicAdd(&(bar)[XB_TMO], 1u); break; } } } } while (0)
; template <bool FIRST>
; DI void xcd_barrier(XcdBarrier& b) {
;     ...
;       XB_SPIN(xb_ld(&bar[XB_XGEN(bx)]) == gen, bar);
;       __builtin_amdgcn_fence(__ATOMIC_ACQUIRE, "agent");
;       asm volatile("s_waitcnt vmcnt(0)" ::: "memory");
.Lsp_d_1:
.LBB0_138:
	s_or_b64 exec, exec, s[8:9]
	s_waitcnt vmcnt(0) lgkmcnt(0)
	buffer_inv sc1
	s_waitcnt vmcnt(0)

; DI unsigned xb_ld(unsigned* p) { return __hip_atomic_load(p, __ATOMIC_RELAXED, __HIP_MEMORY_SCOPE_AGENT); }
; DI unsigned xb_add(unsigned* p, unsigned v) { return __hip_atomic_fetch_add(p, v, __ATOMIC_RELAXED, __HIP_MEMORY_SCOPE_AGENT); }
; #define XB_SPIN(cond, bar) do { unsigned _sp = 0; while (cond) { __builtin_amdgcn_s_sleep(1); \
;     if ((++_sp & 255u) == 0u) { if (xb_ld(&(bar)[XB_TMO])) break; if (_sp > XB_SPIN_CAP) { atomicAdd(&(bar)[XB_TMO], 1u); break; } } } } while (0)
; template <bool FIRST>
; DI void xcd_barrier(XcdBarrier& b) {
;     ...
;   if (threadIdx.x == 0) {
;     unsigned* bar = b.bar;
;     asm volatile("" : "+s"(bar));
;     __builtin_amdgcn_s_waitcnt(0);
;     const unsigned bx = b.st[2];
;     if (FIRST) { unsigned n0, n1; xcd_barrier_complete(bar, bx, n0, n1); b.st[0] = n0; b.st[1] = n1; }
;     const unsigned nloc = b.st[0], nx = b.st[1];
;     const unsigned old = xb_add(&bar[XB_XSUB(bx)], 1u);
;     const unsigned gen = old / nloc;
;     if (old + 1u == (gen + 1u) * nloc) {
;       __builtin_amdgcn_fence(__ATOMIC_RELEASE, "agent");
;       asm volatile("s_waitcnt vmcnt(0)" ::: "memory");
;       const unsigned og = xb_add(&bar[XB_TOP], 1u);
;       const unsigned tg = og / nx;
;       if (og + 1u == (tg + 1u) * nx) xb_add(&bar[XB_TOPGEN], 1u);
;       else XB_SPIN(xb_ld(&bar[XB_TOPGEN]) == tg, bar);
;       __builtin_amdgcn_fence(__ATOMIC_ACQUIRE, "agent");
;       xb_add(&bar[XB_XGEN(bx)], 1u);
;       asm volatile("s_waitcnt vmcnt(0)" ::: "memory");
;     } else {
;       XB_SPIN(xb_ld(&bar[XB_XGEN(bx)]) == gen, bar);
.LBB0_390:
	s_mul_i32 s0, s48, 6
	s_add_i32 s28, s0, 3
	s_cmp_ge_i32 s28, s59
	s_cbranch_scc1 .LBB0_422
	s_waitcnt vmcnt(0)
	s_waitcnt lgkmcnt(0)
	s_barrier
	s_and_saveexec_b64 s[0:1], s[60:61]
	s_cbranch_execz .LBB0_421
	v_readlane_b32 s4, v253, 1
	v_readlane_b32 s5, v253, 2
	s_waitcnt vmcnt(0) expcnt(0) lgkmcnt(0)
	ds_read_b32 v0, v163
	ds_read_b32 v4, v172
	ds_read_b32 v1, v173
	s_waitcnt lgkmcnt(2)
	v_readfirstlane_b32 s2, v0
	s_lshl_b32 s29, s2, 6
	s_add_i32 s2, s29, 0x500
	s_lshl_b64 s[6:7], s[2:3], 2
	s_add_u32 s6, s4, s6
	s_addc_u32 s7, s5, s7
	v_mov_b64_e32 v[2:3], s[6:7]
	flat_atomic_add v2, v[2:3], v174 sc0
	s_waitcnt lgkmcnt(0)
	v_cvt_f32_u32_e32 v0, v4
	v_sub_u32_e32 v3, 0, v4
	v_rcp_iflag_f32_e32 v0, v0
	s_nop 0
	v_mul_f32_e32 v0, 0x4f7ffffe, v0
	v_cvt_u32_f32_e32 v0, v0
	v_mul_lo_u32 v3, v3, v0
	v_mul_hi_u32 v3, v0, v3
	v_add_u32_e32 v0, v0, v3
	s_waitcnt vmcnt(0)
	v_mul_hi_u32 v0, v2, v0
	v_mul_lo_u32 v3, v0, v4
	v_sub_u32_e32 v3, v2, v3
	v_add_u32_e32 v5, 1, v0
	v_cmp_ge_u32_e32 vcc, v3, v4
	v_add_u32_e32 v2, 1, v2
	s_nop 0
	v_cndmask_b32_e32 v0, v0, v5, vcc
	v_sub_u32_e32 v5, v3, v4
	v_cndmask_b32_e32 v3, v3, v5, vcc
	v_add_u32_e32 v5, 1, v0
	v_cmp_ge_u32_e32 vcc, v3, v4
	s_nop 1
	v_cndmask_b32_e32 v0, v0, v5, vcc
	v_mul_lo_u32 v3, v4, v0
	v_add_u32_e32 v3, v3, v4
	v_cmp_ne_u32_e32 vcc, v2, v3
	s_and_saveexec_b64 s[6:7], vcc
	s_xor_b64 s[6:7], exec, s[6:7]
	s_cbranch_execz .LBB0_405
	s_add_i32 s2, s29, 0x900
	s_add_u32 s10, s4, 0x3500
	s_addc_u32 s11, s5, 0
	v_mov_b64_e32 v[2:3], s[10:11]
	global_load_dword v1, v[2:3], off sc1
	s_waitcnt vmcnt(0) lgkmcnt(0)
	v_cmp_eq_u32_e32 vcc, v1, v0
	s_and_saveexec_b64 s[8:9], vcc
	s_cbranch_execz .LBB0_404
	global_load_dword v1, v[2:3], off sc1
	s_sleep 20

; DI unsigned xb_ld(unsigned* p) { return __hip_atomic_load(p, __ATOMIC_RELAXED, __HIP_MEMORY_SCOPE_AGENT); }
; DI unsigned xb_add(unsigned* p, unsigned v) { return __hip_atomic_fetch_add(p, v, __ATOMIC_RELAXED, __HIP_MEMORY_SCOPE_AGENT); }
; #define XB_SPIN(cond, bar) do { unsigned _sp = 0; while (cond) { __builtin_amdgcn_s_sleep(1); \
;     if ((++_sp & 255u) == 0u) { if (xb_ld(&(bar)[XB_TMO])) break; if (_sp > XB_SPIN_CAP) { atomicAdd(&(bar)[XB_TMO], 1u); break; } } } } while (0)
; template <bool FIRST>
; DI void xcd_barrier(XcdBarrier& b) {
;     ...
;   if (threadIdx.x == 0) {
;     unsigned* bar = b.bar;
;     asm volatile("" : "+s"(bar));
;     __builtin_amdgcn_s_waitcnt(0);
;     const unsigned bx = b.st[2];
;     if (FIRST) { unsigned n0, n1; xcd_barrier_complete(bar, bx, n0, n1); b.st[0] = n0; b.st[1] = n1; }
;     const unsigned nloc = b.st[0], nx = b.st[1];
;     const unsigned old = xb_add(&bar[XB_XSUB(bx)], 1u);
;     const unsigned gen = old / nloc;
;     if (old + 1u == (gen + 1u) * nloc) {
;       __builtin_amdgcn_fence(__ATOMIC_RELEASE, "agent");
;       asm volatile("s_waitcnt vmcnt(0)" ::: "memory");
;       const unsigned og = xb_add(&bar[XB_TOP], 1u);
;       const unsigned tg = og / nx;
;       if (og + 1u == (tg + 1u) * nx) xb_add(&bar[XB_TOPGEN], 1u);
;       else XB_SPIN(xb_ld(&bar[XB_TOPGEN]) == tg, bar);
;       __builtin_amdgcn_fence(__ATOMIC_ACQUIRE, "agent");
;       xb_add(&bar[XB_XGEN(bx)], 1u);
;       asm volatile("s_waitcnt vmcnt(0)" ::: "memory");
;     } else {
;       XB_SPIN(xb_ld(&bar[XB_XGEN(bx)]) == gen, bar);
.LBB0_769:
	v_readlane_b32 s48, v254, 17
	s_mul_i32 s0, s48, 6
	s_add_i32 s28, s0, 4
	s_cmp_ge_i32 s28, s59
	v_readlane_b32 s49, v254, 18
	s_cbranch_scc1 .LBB0_801
	s_waitcnt vmcnt(0)
	s_waitcnt lgkmcnt(0)
	s_barrier
	s_and_saveexec_b64 s[0:1], s[60:61]
	s_cbranch_execz .LBB0_800
	v_readlane_b32 s4, v253, 1
	v_readlane_b32 s5, v253, 2
	s_waitcnt vmcnt(0) expcnt(0) lgkmcnt(0)
	ds_read_b32 v0, v163
	ds_read_b32 v4, v172
	ds_read_b32 v1, v173
	s_waitcnt lgkmcnt(2)
	v_readfirstlane_b32 s2, v0
	s_lshl_b32 s29, s2, 6
	s_add_i32 s2, s29, 0x500
	s_lshl_b64 s[6:7], s[2:3], 2
	s_add_u32 s6, s4, s6
	s_addc_u32 s7, s5, s7
	v_mov_b64_e32 v[2:3], s[6:7]
	flat_atomic_add v2, v[2:3], v174 sc0
	s_waitcnt lgkmcnt(0)
	v_cvt_f32_u32_e32 v0, v4
	v_sub_u32_e32 v3, 0, v4
	v_rcp_iflag_f32_e32 v0, v0
	s_nop 0
	v_mul_f32_e32 v0, 0x4f7ffffe, v0
	v_cvt_u32_f32_e32 v0, v0
	v_mul_lo_u32 v3, v3, v0
	v_mul_hi_u32 v3, v0, v3
	v_add_u32_e32 v0, v0, v3
	s_waitcnt vmcnt(0)
	v_mul_hi_u32 v0, v2, v0
	v_mul_lo_u32 v3, v0, v4
	v_sub_u32_e32 v3, v2, v3
	v_add_u32_e32 v5, 1, v0
	v_cmp_ge_u32_e32 vcc, v3, v4
	v_add_u32_e32 v2, 1, v2
	s_nop 0
	v_cndmask_b32_e32 v0, v0, v5, vcc
	v_sub_u32_e32 v5, v3, v4
	v_cndmask_b32_e32 v3, v3, v5, vcc
	v_add_u32_e32 v5, 1, v0
	v_cmp_ge_u32_e32 vcc, v3, v4
	s_nop 1
	v_cndmask_b32_e32 v0, v0, v5, vcc
	v_mul_lo_u32 v3, v4, v0
	v_add_u32_e32 v3, v3, v4
	v_cmp_ne_u32_e32 vcc, v2, v3
	s_and_saveexec_b64 s[6:7], vcc
	s_xor_b64 s[6:7], exec, s[6:7]
	s_cbranch_execz .LBB0_784
	s_add_i32 s2, s29, 0x900
	s_add_u32 s10, s4, 0x3500
	s_addc_u32 s11, s5, 0
	v_mov_b64_e32 v[2:3], s[10:11]
	global_load_dword v1, v[2:3], off sc1
	s_waitcnt vmcnt(0) lgkmcnt(0)
	v_cmp_eq_u32_e32 vcc, v1, v0
	s_and_saveexec_b64 s[8:9], vcc
	s_cbranch_execz .LBB0_783
	global_load_dword v1, v[2:3], off sc1
	s_sleep 20

; DI unsigned xb_ld(unsigned* p) { return __hip_atomic_load(p, __ATOMIC_RELAXED, __HIP_MEMORY_SCOPE_AGENT); }
; DI unsigned xb_add(unsigned* p, unsigned v) { return __hip_atomic_fetch_add(p, v, __ATOMIC_RELAXED, __HIP_MEMORY_SCOPE_AGENT); }
; #define XB_SPIN(cond, bar) do { unsigned _sp = 0; while (cond) { __builtin_amdgcn_s_sleep(1); \
;     if ((++_sp & 255u) == 0u) { if (xb_ld(&(bar)[XB_TMO])) break; if (_sp > XB_SPIN_CAP) { atomicAdd(&(bar)[XB_TMO], 1u); break; } } } } while (0)
; template <bool FIRST>
; DI void xcd_barrier(XcdBarrier& b) {
;     ...
;   if (threadIdx.x == 0) {
;     unsigned* bar = b.bar;
;     asm volatile("" : "+s"(bar));
;     __builtin_amdgcn_s_waitcnt(0);
;     const unsigned bx = b.st[2];
;     if (FIRST) { unsigned n0, n1; xcd_barrier_complete(bar, bx, n0, n1); b.st[0] = n0; b.st[1] = n1; }
;     const unsigned nloc = b.st[0], nx = b.st[1];
;     const unsigned old = xb_add(&bar[XB_XSUB(bx)], 1u);
;     const unsigned gen = old / nloc;
;     if (old + 1u == (gen + 1u) * nloc) {
;       __builtin_amdgcn_fence(__ATOMIC_RELEASE, "agent");
;       asm volatile("s_waitcnt vmcnt(0)" ::: "memory");
;       const unsigned og = xb_add(&bar[XB_TOP], 1u);
;       const unsigned tg = og / nx;
;       if (og + 1u == (tg + 1u) * nx) xb_add(&bar[XB_TOPGEN], 1u);
;       else XB_SPIN(xb_ld(&bar[XB_TOPGEN]) == tg, bar);
;       __builtin_amdgcn_fence(__ATOMIC_ACQUIRE, "agent");
;       xb_add(&bar[XB_XGEN(bx)], 1u);
;       asm volatile("s_waitcnt vmcnt(0)" ::: "memory");
;     } else {
;       XB_SPIN(xb_ld(&bar[XB_XGEN(bx)]) == gen, bar);
.LBB0_1018:
	v_readlane_b32 s48, v254, 17
	s_mul_i32 s0, s48, 6
	s_add_i32 s0, s0, 5
	v_readlane_b32 s72, v254, 15
	s_cmp_ge_i32 s0, s59
	v_readlane_b32 s73, v254, 16
	v_readlane_b32 s49, v254, 18
	s_cbranch_scc1 .LBB0_1050
	s_waitcnt vmcnt(0)
	s_waitcnt lgkmcnt(0)
	s_barrier
	s_and_saveexec_b64 s[0:1], s[60:61]
	s_cbranch_execz .LBB0_1049
	v_readlane_b32 s4, v253, 1
	v_readlane_b32 s5, v253, 2
	s_waitcnt vmcnt(0) expcnt(0) lgkmcnt(0)
	ds_read_b32 v0, v163
	ds_read_b32 v4, v172
	ds_read_b32 v1, v173
	s_waitcnt lgkmcnt(2)
	v_readfirstlane_b32 s2, v0
	s_lshl_b32 s28, s2, 6
	s_add_i32 s2, s28, 0x500
	s_lshl_b64 s[6:7], s[2:3], 2
	s_add_u32 s6, s4, s6
	s_addc_u32 s7, s5, s7
	v_mov_b64_e32 v[2:3], s[6:7]
	flat_atomic_add v2, v[2:3], v174 sc0
	s_waitcnt lgkmcnt(0)
	v_cvt_f32_u32_e32 v0, v4
	v_sub_u32_e32 v3, 0, v4
	v_rcp_iflag_f32_e32 v0, v0
	s_nop 0
	v_mul_f32_e32 v0, 0x4f7ffffe, v0
	v_cvt_u32_f32_e32 v0, v0
	v_mul_lo_u32 v3, v3, v0
	v_mul_hi_u32 v3, v0, v3
	v_add_u32_e32 v0, v0, v3
	s_waitcnt vmcnt(0)
	v_mul_hi_u32 v0, v2, v0
	v_mul_lo_u32 v3, v0, v4
	v_sub_u32_e32 v3, v2, v3
	v_add_u32_e32 v5, 1, v0
	v_cmp_ge_u32_e32 vcc, v3, v4
	v_add_u32_e32 v2, 1, v2
	s_nop 0
	v_cndmask_b32_e32 v0, v0, v5, vcc
	v_sub_u32_e32 v5, v3, v4
	v_cndmask_b32_e32 v3, v3, v5, vcc
	v_add_u32_e32 v5, 1, v0
	v_cmp_ge_u32_e32 vcc, v3, v4
	s_nop 1
	v_cndmask_b32_e32 v0, v0, v5, vcc
	v_mul_lo_u32 v3, v4, v0
	v_add_u32_e32 v3, v3, v4
	v_cmp_ne_u32_e32 vcc, v2, v3
	s_and_saveexec_b64 s[6:7], vcc
	s_xor_b64 s[6:7], exec, s[6:7]
	s_cbranch_execz .LBB0_1033
	s_add_i32 s2, s28, 0x900
	s_add_u32 s10, s4, 0x3500
	s_addc_u32 s11, s5, 0
	v_mov_b64_e32 v[2:3], s[10:11]
	global_load_dword v1, v[2:3], off sc1
	s_waitcnt vmcnt(0) lgkmcnt(0)
	v_cmp_eq_u32_e32 vcc, v1, v0
	s_and_saveexec_b64 s[8:9], vcc
	s_cbranch_execz .LBB0_1032
	global_load_dword v1, v[2:3], off sc1
	s_sleep 20

; DI unsigned xb_ld(unsigned* p) { return __hip_atomic_load(p, __ATOMIC_RELAXED, __HIP_MEMORY_SCOPE_AGENT); }
; DI unsigned xb_add(unsigned* p, unsigned v) { return __hip_atomic_fetch_add(p, v, __ATOMIC_RELAXED, __HIP_MEMORY_SCOPE_AGENT); }
; #define XB_SPIN(cond, bar) do { unsigned _sp = 0; while (cond) { __builtin_amdgcn_s_sleep(1); \
;     if ((++_sp & 255u) == 0u) { if (xb_ld(&(bar)[XB_TMO])) break; if (_sp > XB_SPIN_CAP) { atomicAdd(&(bar)[XB_TMO], 1u); break; } } } } while (0)
; template <bool FIRST>
; DI void xcd_barrier(XcdBarrier& b) {
;     ...
;   if (threadIdx.x == 0) {
;     unsigned* bar = b.bar;
;     asm volatile("" : "+s"(bar));
;     __builtin_amdgcn_s_waitcnt(0);
;     const unsigned bx = b.st[2];
;     if (FIRST) { unsigned n0, n1; xcd_barrier_complete(bar, bx, n0, n1); b.st[0] = n0; b.st[1] = n1; }
;     const unsigned nloc = b.st[0], nx = b.st[1];
;     const unsigned old = xb_add(&bar[XB_XSUB(bx)], 1u);
;     const unsigned gen = old / nloc;
;     if (old + 1u == (gen + 1u) * nloc) {
;       __builtin_amdgcn_fence(__ATOMIC_RELEASE, "agent");
;       asm volatile("s_waitcnt vmcnt(0)" ::: "memory");
;       const unsigned og = xb_add(&bar[XB_TOP], 1u);
;       const unsigned tg = og / nx;
;       if (og + 1u == (tg + 1u) * nx) xb_add(&bar[XB_TOPGEN], 1u);
;       else XB_SPIN(xb_ld(&bar[XB_TOPGEN]) == tg, bar);
;       __builtin_amdgcn_fence(__ATOMIC_ACQUIRE, "agent");
;       xb_add(&bar[XB_XGEN(bx)], 1u);
;       asm volatile("s_waitcnt vmcnt(0)" ::: "memory");
;     } else {
;       XB_SPIN(xb_ld(&bar[XB_XGEN(bx)]) == gen, bar);
.LBB0_1100:
	v_readlane_b32 s0, v254, 14
	s_add_i32 s0, s0, 7
	s_cmp_ge_i32 s0, s59
	s_cbranch_scc1 .Ltr_109
	s_waitcnt vmcnt(0)
	s_waitcnt lgkmcnt(0)
	s_barrier
	s_and_saveexec_b64 s[0:1], s[60:61]
	s_cbranch_execz .Ltr_108
	v_readlane_b32 s4, v253, 1
	v_readlane_b32 s5, v253, 2
	s_waitcnt vmcnt(0) expcnt(0) lgkmcnt(0)
	ds_read_b32 v0, v163
	ds_read_b32 v4, v172
	ds_read_b32 v1, v173
	s_waitcnt lgkmcnt(2)
	v_readfirstlane_b32 s2, v0
	s_lshl_b32 s28, s2, 6
	s_add_i32 s2, s28, 0x500
	s_lshl_b64 s[6:7], s[2:3], 2
	s_add_u32 s6, s4, s6
	s_addc_u32 s7, s5, s7
	v_mov_b64_e32 v[2:3], s[6:7]
	flat_atomic_add v2, v[2:3], v174 sc0
	s_waitcnt lgkmcnt(0)
	v_cvt_f32_u32_e32 v0, v4
	v_sub_u32_e32 v3, 0, v4
	v_rcp_iflag_f32_e32 v0, v0
	s_nop 0
	v_mul_f32_e32 v0, 0x4f7ffffe, v0
	v_cvt_u32_f32_e32 v0, v0
	v_mul_lo_u32 v3, v3, v0
	v_mul_hi_u32 v3, v0, v3
	v_add_u32_e32 v0, v0, v3
	s_waitcnt vmcnt(0)
	v_mul_hi_u32 v0, v2, v0
	v_mul_lo_u32 v3, v0, v4
	v_sub_u32_e32 v3, v2, v3
	v_add_u32_e32 v5, 1, v0
	v_cmp_ge_u32_e32 vcc, v3, v4
	v_add_u32_e32 v2, 1, v2
	s_nop 0
	v_cndmask_b32_e32 v0, v0, v5, vcc
	v_sub_u32_e32 v5, v3, v4
	v_cndmask_b32_e32 v3, v3, v5, vcc
	v_add_u32_e32 v5, 1, v0
	v_cmp_ge_u32_e32 vcc, v3, v4
	s_nop 1
	v_cndmask_b32_e32 v0, v0, v5, vcc
	v_mul_lo_u32 v3, v4, v0
	v_add_u32_e32 v3, v3, v4
	v_cmp_ne_u32_e32 vcc, v2, v3
	s_and_saveexec_b64 s[6:7], vcc
	s_xor_b64 s[6:7], exec, s[6:7]
	s_cbranch_execz .LBB0_1115
	s_add_i32 s2, s28, 0x900
	s_add_u32 s10, s4, 0x3500
	s_addc_u32 s11, s5, 0
	v_mov_b64_e32 v[2:3], s[10:11]
	global_load_dword v1, v[2:3], off sc1
	s_waitcnt vmcnt(0) lgkmcnt(0)
	v_cmp_eq_u32_e32 vcc, v1, v0
	s_and_saveexec_b64 s[8:9], vcc
	s_cbranch_execz .LBB0_1114
	global_load_dword v1, v[2:3], off sc1
	s_sleep 20
